# v53 + ffn_in GEMMs: each XCD walks one whole 8-panel group (all XCDs on the same weight column tiles each round), context panels fill the 12th round
# speedup vs baseline: 1.0053x; 1.0053x over previous
;     __device__ __forceinline__ unsigned code(int i, unsigned& ko_) const { Unit u; u.pm = 0; u.pn = 0; u.ko = 0; u.nk = 0; u.ks = 0; const bool ok = next(i, u); ko_ = (unsigned)u.ko; return ok ? (0x80000000u | ((unsigned)u.nk << 16) | ((unsigned)u.pm << 8) | (unsigned)u.pn) : 0u; }
;     __host__ __device__ __forceinline__ bool next(int i, Unit& u) const {
;         const long L = (long)i * G + c; if (L >= nwg) return false;
;         int wgid = (int)L; { const int q = nwg / NXCD, r = nwg % NXCD, xcd = wgid % NXCD, off = wgid / NXCD; wgid = (xcd < r ? xcd * (q + 1) : r * (q + 1) + (xcd - r) * q) + off; }
;         const int nig = WGM * nN, gid = wgid / nig, fm = gid * WGM, gsz = (nM - fm) < WGM ? (nM - fm) : WGM;
;         u.pm = fm + ((wgid % nig) % gsz); u.pn = (wgid % nig) / gsz; u.ko = 0; u.nk = nk; return true;
;     }
;         const int pair = (K / 64) / (nks_ / 2); t1 = ((pair / 2 + 1) / 2) * 2; t2 = pair - t1; }
;     __device__ __forceinline__ unsigned code(int i, unsigned& ko_) const {
;         const int L = i * lat.G + lat.c; if (L < nlat) return lat.code(i, ko_);
;         const int Lp = L - nlat; if (Lp >= nsp) { ko_ = 0u; return 0u; }
;         const int r = Lp / nks, ks = Lp % nks; ko_ = (unsigned)(((ks >> 1) * (t1 + t2) + (ks & 1) * t1) * 64);
;         return 0x80000000u | ((unsigned)ks << 24) | ((unsigned)((ks & 1) ? t2 : t1) << 16) | ((unsigned)(64 + (r & 3)) << 8) | (unsigned)(r >> 2);
; template <class Epi, class Sched, bool ALIGN_EPI = false, bool SP2 = false>
; __device__ __forceinline__ void gemm_phase(PG8_LAS unsigned char* lds, const Gemm g, const Sched& S, const Epi& E, const int wv) {
;     ...
;     bool ok0_; cur.pm = 0; cur.pn = 0; cur.ko = 0; cur.nk = 4; cur.ks = 0; PG8_NEXT(0, cur, ok0_);
.LBB0_250:
	s_or_b64 exec, exec, s[36:37]
	s_cmpk_lt_i32 s92, 0xbb0
	s_cselect_b64 s[0:1], -1, 0
	v_writelane_b32 v254, s0, 6
	s_ashr_i32 s90, s92, 31
	s_bfe_u32 s2, s92, 0x20001
	v_writelane_b32 v254, s1, 7
	s_lshr_b32 s0, s90, 29
	s_and_b32 s3, s92, 1
	s_add_i32 s0, s92, s0
	s_mul_i32 s2, s2, 22
	s_mul_i32 s4, s3, 12
	s_ashr_i32 s17, s0, 3
	s_and_b32 s0, s0, -8
	s_and_b32 s1, s92, 7
	s_add_i32 s2, s2, s4
	s_sub_i32 s18, s92, s0
	s_and_b32 s0, s92, 0x7fffff00
	s_lshl_b32 s2, s2, 6
	s_lshl_b32 s1, s1, 24
	s_cmp_eq_u32 s3, 0
	s_mov_b32 s3, 0xc0000
	s_cselect_b32 s3, s3, 0xa0000
	s_lshl_b32 s4, s92, 5
	s_and_b32 s4, s4, 0x300
	s_bfe_u32 s5, s92, 0x30005
	s_or_b32 s4, s5, s4
	s_or_b32 s1, s4, s1
	s_or_b32 s3, s1, s3
	s_or_b32 s3, s3, 0x80004000
	s_lshl_b32 s4, s18, 6
	s_lshl_b32 s6, s92, 9
	s_lshl_b32 s5, s92, 2
	s_cmpk_lt_i32 s5, 0x400
	v_writelane_b32 v254, s5, 8
	s_cselect_b64 s[8:9], -1, 0
	v_writelane_b32 v254, s8, 9
	s_lshl_b32 s7, s92, 24
	s_and_b32 s7, s7, 0x3000000
	v_writelane_b32 v254, s9, 10
	s_lshl_b32 s8, s92, 6
	s_bfe_u32 s10, s92, 0x40004
	s_and_b32 s9, s8, 0x300
	s_or_b32 s7, s7, s10
	s_or_b32 s7, s7, s9
	s_add_i32 s5, s92, 0xfffffd00
	v_writelane_b32 v254, s6, 11
	s_and_b32 s6, s6, 0x600
	s_or_b32 s7, s7, 0x80084000
	s_cmpk_lt_i32 s92, 0xcc
	s_cselect_b64 s[10:11], -1, 0
	s_lshl_b32 s12, s94, 8
	s_add_i32 s59, s12, 0
	s_lshl_b32 s12, s94, 12
	v_writelane_b32 v254, s10, 12
	s_add_i32 s12, s12, 0
	s_add_i32 s12, s12, 0x14800
	v_writelane_b32 v254, s11, 13
	v_writelane_b32 v254, s12, 14
	s_add_i32 s12, s92, 0xfffffe00
	s_mul_i32 s9, s18, 25
	v_writelane_b32 v254, s12, 15
	s_lshl_b32 s12, s92, 8
	s_add_i32 s9, s9, 4
	s_add_i32 s10, s92, 0xcc
	s_add_i32 s11, s92, 0xdc
	s_add_i32 s95, s59, 0x10000
	s_lshl_b32 s19, s94, 5
	s_add_i32 s59, s59, 0x14000
	s_and_b32 s12, s12, 0x700
	s_or_b32 s1, s1, 0x80044000
	v_writelane_b32 v254, s12, 16
	s_cmp_lt_i32 s18, 0
	s_movk_i32 s12, 0x177
	v_writelane_b32 v254, s1, 17
	s_mul_i32 s1, s18, 0x41
	s_cselect_b32 s12, s12, 0x176
	s_mul_i32 s12, s18, s12
	s_cselect_b32 s1, s1, s4
	s_movk_i32 s4, 0x61
	s_cselect_b32 s4, s4, 0x60
	s_add_i32 s12, s12, s17
	s_mul_hi_i32 s13, s12, 0x2e8ba2e9
	s_lshr_b32 s14, s13, 31
	s_ashr_i32 s13, s13, 6
	s_add_i32 s13, s13, s14
	s_mul_i32 s14, s13, 0x160
	s_lshl_b32 s13, s13, 3
	s_sub_i32 s15, 0x44, s13
	s_min_u32 s15, s15, 8
	s_sub_i32 s12, s12, s14
	s_cmpk_eq_i32 s0, 0x200
	s_cselect_b32 s2, s2, 0
	s_cselect_b32 s3, s3, 0
	s_add_i32 s0, s1, s17
	s_ashr_i32 s1, s0, 31
	s_lshr_b32 s1, s1, 26
	s_add_i32 s1, s0, s1
	s_and_b32 s14, s1, 0xffc0
	s_sub_i32 s0, s0, s14
	s_bfe_i32 s14, s0, 0x80000
	s_bfe_u32 s14, s14, 0x3000c
	s_add_i32 s14, s0, s14
	s_bfe_i32 s16, s14, 0x80000
	s_and_b32 s14, s14, 0xf8
	s_sub_i32 s0, s0, s14
	s_sext_i32_i8 s0, s0
	s_lshl_b32 s1, s1, 5
	s_sext_i32_i16 s16, s16
	s_and_b32 s1, s1, 0xfffff800
	s_lshl_b32 s0, s0, 8
	s_ashr_i32 s14, s16, 3
	s_add_i32 s0, s0, s1
	s_or_b32 s0, s0, s14
	s_or_b32 s14, s0, 0x80580000
	s_cmpk_lt_u32 s5, 0xc0
	s_mul_i32 s4, s18, s4
	s_cselect_b32 s1, s6, 0
	s_cselect_b32 s5, s7, 0
	s_add_i32 s4, s4, s17
	s_mul_hi_i32 s6, s4, 0x2aaaaaab
	s_lshr_b32 s7, s6, 31
	s_ashr_i32 s6, s6, 4
	s_add_i32 s6, s6, s7
	s_mul_i32 s7, s6, 0x60
	s_sub_i32 s4, s4, s7
	s_bfe_i32 s7, s4, 0x80000
	s_bfe_u32 s7, s7, 0x3000c
	s_add_i32 s7, s4, s7
	s_bfe_i32 s16, s7, 0x80000
	s_and_b32 s7, s7, 0xf8
	s_sub_i32 s4, s4, s7
	s_sext_i32_i8 s4, s4
	s_sext_i32_i16 s16, s16
	s_lshl_b32 s6, s6, 11
	s_lshl_b32 s4, s4, 8
	s_ashr_i32 s7, s16, 3
	s_add_i32 s4, s4, s6
	s_or_b32 s4, s4, s7
	s_or_b32 s4, s4, 0x80200000
	s_cmp_lt_i32 s18, 4
	s_mul_i32 s6, s18, 26
	s_cselect_b32 s6, s6, s9
	s_add_i32 s6, s6, s17
	s_mul_hi_i32 s7, s6, 0x2aaaaaab
	s_lshr_b32 s9, s7, 31
	s_ashr_i32 s7, s7, 2
	s_add_i32 s7, s7, s9
	s_lshl_b32 s9, s7, 3
	s_sub_i32 s16, 0x44, s9
	s_mul_i32 s7, s7, 24
	s_min_u32 s16, s16, 8
; #define GEMM(g, S, E) pg8::gemm_phase<decltype(E), decltype(S), true, true>((LAS unsigned char*)lds, g, S, E, wv)
; #define PH_BEGIN KParams kp = kargs(); unsigned char* ws = kp->ws; (void)ws; const int G = gridDim.x, bid = blockIdx.x; (void)G; (void)bid; \
;     const unsigned char* wl = ws + WS_W + (size_t)layer * W_LAYER; (void)wl; const float* mod = WSP(float, WS_MOD) + (size_t)layer * 5 * MODW; (void)mod; pg8::StaticOrder S; (void)S;
;     __host__ __device__ __forceinline__ bool next(int i, Unit& u) const {
;         const long L = (long)i * G + c; if (L >= nwg) return false;
;         int wgid = (int)L; { const int q = nwg / NXCD, r = nwg % NXCD, xcd = wgid % NXCD, off = wgid / NXCD; wgid = (xcd < r ? xcd * (q + 1) : r * (q + 1) + (xcd - r) * q) + off; }
;         const int nig = WGM * nN, gid = wgid / nig, fm = gid * WGM, gsz = (nM - fm) < WGM ? (nM - fm) : WGM;
;         u.pm = fm + ((wgid % nig) % gsz); u.pn = (wgid % nig) / gsz; u.ko = 0; u.nk = nk; return true;
;     }
; __global__ void __launch_bounds__(512, 2) fwd_kernel(Params p) {
;     ...
;         { PH_BEGIN pg8::Gemm g{WSP(bf16_t, WS_XN), (const bf16_t*)(wl + W_F1IN), R, 2 * DFF, D, LDP, D}; S.init(R, 2 * DFF, G, bid, D);
;             EpiSwiglu E{WSP(bf16_t, WS_ACT), WSP(float, WS_RINV), WSP(float, WS_SW) + (size_t)(layer * 3 + 0) * 5 * SWLD}; GEMM(g, S, E); }
	s_sub_i32 s6, s6, s7
	s_or_b32 s0, s0, 0x80200000
	v_writelane_b32 v254, s17, 18
	s_cmpk_lt_i32 s92, 0x300
	v_writelane_b32 v254, s0, 19
	s_cselect_b32 s0, 0, s1
	v_writelane_b32 v254, s0, 20
	v_cvt_f32_ubyte0_e32 v1, s15
	v_cvt_f32_i32_e32 v0, s12
	v_writelane_b32 v254, s1, 21
	s_cselect_b32 s0, s4, s5
	v_writelane_b32 v254, s0, 22
	v_writelane_b32 v254, s18, 23
	s_lshr_b32 s0, s18, 31
	v_writelane_b32 v254, s0, 24
	s_mul_i32 s4, s94, 0x21000
	v_writelane_b32 v254, s4, 25
	s_cmpk_lt_i32 s92, 0x200
	v_writelane_b32 v254, s19, 26
	s_mul_hi_u32 s4, s19, 0x1080
	s_cselect_b64 s[0:1], -1, 0
	v_writelane_b32 v254, s4, 27
	v_rcp_iflag_f32_e32 v2, v1
	v_writelane_b32 v254, s0, 28
	s_mov_b64 s[4:5], -1
	s_movk_i32 s73, 0x600
	v_writelane_b32 v254, s1, 29
	s_and_b64 s[0:1], s[0:1], exec
	s_cselect_b32 s0, 0, s2
	v_writelane_b32 v254, s0, 30
	v_mul_f32_e32 v2, v0, v2
	v_trunc_f32_e32 v2, v2
	v_writelane_b32 v254, s1, 31
	s_cselect_b32 s0, s14, s3
	v_writelane_b32 v254, s0, 32
	s_cselect_b32 s0, s14, 0
	v_fma_f32 v0, -v2, v1, v0
	v_cvt_i32_f32_e32 v2, v2
	v_writelane_b32 v254, s0, 33
	s_and_b32 s0, s92, 7
	s_lshl_b32 s0, s0, 3
	s_lshr_b32 s1, s92, 6
	s_add_i32 s0, s0, s1
	s_lshl_b32 s0, s0, 8
	s_bfe_u32 s1, s92, 0x30003
	s_or_b32 s0, s0, s1
	s_or_b32 s0, s0, 0x80580000
	v_writelane_b32 v254, s0, 32
	v_writelane_b32 v254, s0, 33
	s_ashr_i32 s0, s12, 30
	s_or_b32 s2, s0, 1
	v_cmp_ge_f32_e64 s[0:1], |v0|, v1
	s_and_b64 s[0:1], s[0:1], exec
	s_cselect_b32 s0, s2, 0
	v_readfirstlane_b32 s1, v2
	s_add_i32 s0, s1, s0
	v_cvt_f32_ubyte0_e32 v1, s16
	s_sext_i32_i16 s1, s0
	s_mul_i32 s0, s0, s15
	v_cvt_f32_i32_e32 v0, s6
	v_rcp_iflag_f32_e32 v2, v1
	s_sub_i32 s0, s12, s0
	s_sext_i32_i16 s0, s0
	s_add_i32 s13, s13, s0
	s_lshl_b32 s0, s13, 8
	v_mul_f32_e32 v2, v0, v2
	s_or_b32 s0, s0, s1
	v_trunc_f32_e32 v2, v2
	s_or_b32 s0, s0, 0x80200000
	v_fma_f32 v0, -v2, v1, v0
	v_cvt_i32_f32_e32 v2, v2
	s_and_b32 s0, s92, 7
	s_lshl_b32 s0, s0, 3
	s_bfe_u32 s1, s92, 0x30003
	s_add_i32 s0, s0, s1
	s_lshl_b32 s0, s0, 8
	s_lshr_b32 s1, s92, 6
	s_or_b32 s0, s0, s1
	s_or_b32 s0, s0, 0x80200000
	v_writelane_b32 v254, s0, 34
	s_ashr_i32 s0, s6, 30
	s_or_b32 s2, s0, 1
	v_cmp_ge_f32_e64 s[0:1], |v0|, v1
	s_and_b64 s[0:1], s[0:1], exec
	s_cselect_b32 s0, s2, 0
	v_readfirstlane_b32 s1, v2
	s_add_i32 s0, s1, s0
	s_sext_i32_i8 s1, s0
	s_mul_i32 s0, s0, s16
	s_sub_i32 s0, s6, s0
	s_sext_i32_i8 s0, s0
	s_add_i32 s9, s9, s0
	s_lshl_b32 s0, s9, 8
	s_or_b32 s0, s0, s1
	s_or_b32 s0, s0, 0x80080000
	v_writelane_b32 v254, s0, 35
	s_ashr_i32 s0, s10, 31
	v_writelane_b32 v254, s0, 36
	s_abs_i32 s0, s10
	v_writelane_b32 v254, s0, 37
	s_ashr_i32 s0, s11, 31
	v_writelane_b32 v254, s0, 38
	s_abs_i32 s0, s11
	v_writelane_b32 v254, s0, 39
	s_or_b32 s0, s8, 7
	v_writelane_b32 v254, s0, 40
	s_add_i32 s0, 0, 0x25ff0
	v_writelane_b32 v254, s0, 41
	s_add_i32 s0, 0, 0x25ff4
	v_writelane_b32 v254, s0, 42
	s_mov_b32 s2, 0
	v_writelane_b32 v254, s2, 43
	v_writelane_b32 v254, s4, 45
	s_movk_i32 s3, 0x1800
	s_mov_b32 s2, s92
	v_writelane_b32 v254, s5, 46
	v_writelane_b32 v254, s96, 47
	s_movk_i32 s66, 0x1080
	v_mov_b32_e32 v193, 0
	v_writelane_b32 v254, s97, 48
	v_writelane_b32 v254, s2, 49
	v_mov_b32_e32 v243, 1
	v_mov_b32_e32 v241, 0x358637bd
	v_writelane_b32 v254, s3, 50
	v_writelane_b32 v254, s94, 51
	s_mov_b32 s68, 0x800000
	s_mov_b32 s79, 0xc00000
	s_movk_i32 s91, 0x1000
	s_mov_b32 s1, 0x42b504f3
	s_mov_b32 s0, 0x1c8ff000
	s_mov_b32 s67, 0x1c07f000
	s_mov_b32 s61, 0x1c907000
	s_mov_b32 s64, 0x1c087000
	s_mov_b32 s69, 0x42ddb3d8
	s_mov_b32 s38, 0x2048f000
	s_mov_b32 s39, 0x1eb1f000
	s_mov_b32 s63, 0x2049f000
	s_mov_b32 s82, 0x1eb37000
	s_mov_b64 s[74:75], 0x20000
	s_mov_b32 s76, 0x3e0293ee
	s_mov_b32 s78, 0x3dd53b94
	s_mov_b64 s[80:81], 0x30000
	s_mov_b32 s41, 0
	v_writelane_b32 v254, s90, 52
	s_waitcnt lgkmcnt(0)
	s_barrier
	s_branch .LBB0_254

;     __host__ __device__ __forceinline__ bool next(int i, Unit& u) const {
;         const long L = (long)i * G + c; if (L >= nwg) return false;
;         int wgid = (int)L; { const int q = nwg / NXCD, r = nwg % NXCD, xcd = wgid % NXCD, off = wgid / NXCD; wgid = (xcd < r ? xcd * (q + 1) : r * (q + 1) + (xcd - r) * q) + off; }
;         const int nig = WGM * nN, gid = wgid / nig, fm = gid * WGM, gsz = (nM - fm) < WGM ? (nM - fm) : WGM;
;         u.pm = fm + ((wgid % nig) % gsz); u.pn = (wgid % nig) / gsz; u.ko = 0; u.nk = nk; return true;
;     }
; template <class Epi, class Sched, bool ALIGN_EPI = false, bool SP2 = false>
; __device__ __forceinline__ void gemm_phase(PG8_LAS unsigned char* lds, const Gemm g, const Sched& S, const Epi& E, const int wv) {
;     ...
;         nxt = cur; bool has_next; PG8_NEXT(ui + 1, nxt, has_next);
.LBB0_262:
	s_add_i32 s54, s54, 1
	s_mul_i32 s2, s54, s53
	s_mul_hi_u32 s12, s54, s70
	s_add_i32 s2, s12, s2
	s_mul_i32 s12, s54, s70
	s_add_u32 s12, s12, s92
	s_addc_u32 s13, s2, s90
	v_mov_b64_e32 v[0:1], 0xbaf
	v_cmp_gt_i64_e32 vcc, s[12:13], v[0:1]
	s_mov_b32 s14, 0
	s_cbranch_vccnz .LBB0_264
	s_ashr_i32 s2, s12, 31
	s_lshr_b32 s2, s2, 29
	s_add_i32 s2, s12, s2
	s_ashr_i32 s13, s2, 3
	s_and_b32 s2, s2, -8
	s_sub_i32 s2, s12, s2
	s_cmpk_lt_i32 s13, 0x160
	s_cselect_b32 s12, 0x160, 22
	s_mul_i32 s2, s2, s12
	s_cselect_b32 s12, 0, 0x9a0
	s_add_i32 s2, s2, s13
	s_add_i32 s2, s2, s12
	s_mul_hi_i32 s12, s2, 0x2e8ba2e9
	s_lshr_b32 s13, s12, 31
	s_ashr_i32 s12, s12, 6
	s_add_i32 s12, s12, s13
	s_lshl_b32 s13, s12, 3
	s_sub_i32 s14, 0x44, s13
	s_min_i32 s14, s14, 8
	s_abs_i32 s15, s14
	v_cvt_f32_u32_e32 v0, s15
	s_sub_i32 s17, 0, s15
	s_mulk_i32 s12, 0x160
	s_sub_i32 s2, s2, s12
	v_rcp_iflag_f32_e32 v0, v0
	s_abs_i32 s12, s2
	s_xor_b32 s16, s2, s14
	s_ashr_i32 s16, s16, 31
	v_mul_f32_e32 v0, 0x4f7ffffe, v0
	v_cvt_u32_f32_e32 v0, v0
	s_nop 0
	v_readfirstlane_b32 s22, v0
	s_mul_i32 s17, s17, s22
	s_mul_hi_u32 s17, s22, s17
	s_add_i32 s22, s22, s17
	s_mul_hi_u32 s17, s12, s22
	s_mul_i32 s22, s17, s15
	s_sub_i32 s12, s12, s22
	s_add_i32 s23, s17, 1
	s_sub_i32 s22, s12, s15
	s_cmp_ge_u32 s12, s15
	s_cselect_b32 s17, s23, s17
	s_cselect_b32 s12, s22, s12
	s_add_i32 s22, s17, 1
	s_cmp_ge_u32 s12, s15
	s_cselect_b32 s12, s22, s17
	s_xor_b32 s12, s12, s16
	s_sub_i32 s12, s12, s16
	s_mul_i32 s14, s12, s14
	s_sub_i32 s2, s2, s14
	s_add_i32 s13, s13, s2
	s_lshl_b32 s2, s13, 8
	s_or_b32 s2, s12, s2
	s_or_b32 s14, s2, 0x80200000

; #define GEMM(g, S, E) pg8::gemm_phase<decltype(E), decltype(S), true, true>((LAS unsigned char*)lds, g, S, E, wv)
; #define PH_BEGIN KParams kp = kargs(); unsigned char* ws = kp->ws; (void)ws; const int G = gridDim.x, bid = blockIdx.x; (void)G; (void)bid; \
;     const unsigned char* wl = ws + WS_W + (size_t)layer * W_LAYER; (void)wl; const float* mod = WSP(float, WS_MOD) + (size_t)layer * 5 * MODW; (void)mod; pg8::StaticOrder S; (void)S;
;     __host__ __device__ __forceinline__ bool next(int i, Unit& u) const {
;         const long L = (long)i * G + c; if (L >= nwg) return false;
;         int wgid = (int)L; { const int q = nwg / NXCD, r = nwg % NXCD, xcd = wgid % NXCD, off = wgid / NXCD; wgid = (xcd < r ? xcd * (q + 1) : r * (q + 1) + (xcd - r) * q) + off; }
;         const int nig = WGM * nN, gid = wgid / nig, fm = gid * WGM, gsz = (nM - fm) < WGM ? (nM - fm) : WGM;
;         u.pm = fm + ((wgid % nig) % gsz); u.pn = (wgid % nig) / gsz; u.ko = 0; u.nk = nk; return true;
;     }
; __global__ void __launch_bounds__(512, 2) fwd_kernel(Params p) {
;     ...
;         { PH_BEGIN pg8::Gemm g{WSP(bf16_t, WS_XN), (const bf16_t*)(wl + W_F2IN), Mo, 2 * DFF, D, LDP, D}; S.init(Mo, 2 * DFF, G, bid, D);
;             EpiSwiglu E{WSP(bf16_t, WS_ACT), WSP(float, WS_RINV), WSP(float, WS_SW) + (size_t)(layer * 3 + 2) * 5 * SWLD}; GEMM(g, S, E); }
.LBB0_1161:
	s_or_b64 exec, exec, s[42:43]
	v_readlane_b32 s4, v254, 45
	s_mov_b64 s[6:7], s[96:97]
	v_readlane_b32 s5, v254, 46
	s_waitcnt lgkmcnt(0)
	s_barrier
	s_load_dwordx2 s[14:15], s[6:7], 0xb8
	s_and_b64 s[4:5], s[4:5], exec
	s_cselect_b32 s4, 0x44, 64
	s_mul_i32 s6, s4, 44
	s_mov_b32 s7, s94
	s_mov_b32 s8, s94
	s_cmp_ge_i32 s92, s6
	s_mov_b32 s10, 0
	v_mbcnt_lo_u32_b32 v0, -1, 0
	v_mbcnt_hi_u32_b32 v0, -1, v0
	s_cbranch_scc1 .LBB0_1163
	s_lshr_b32 s2, s6, 3
	v_readlane_b32 s5, v254, 24
	s_or_b32 s2, s2, s5
	s_movk_i32 s2, 0x160
	v_readlane_b32 s5, v254, 23
	s_mul_i32 s2, s2, s5
	v_readlane_b32 s5, v254, 18
	s_add_i32 s2, s2, s5
	s_mul_hi_i32 s5, s2, 0x2e8ba2e9
	s_lshr_b32 s9, s5, 31
	s_ashr_i32 s5, s5, 6
	s_add_i32 s5, s5, s9
	s_lshl_b32 s9, s5, 3
	s_sub_i32 s10, s4, s9
	s_min_i32 s10, s10, 8
	s_abs_i32 s11, s10
	v_cvt_f32_u32_e32 v1, s11
	s_sub_i32 s13, 0, s11
	s_mulk_i32 s5, 0x160
	s_sub_i32 s2, s2, s5
	v_rcp_iflag_f32_e32 v1, v1
	s_abs_i32 s5, s2
	s_xor_b32 s12, s2, s10
	s_ashr_i32 s12, s12, 31
	v_mul_f32_e32 v1, 0x4f7ffffe, v1
	v_cvt_u32_f32_e32 v1, v1
	s_nop 0
	v_readfirstlane_b32 s16, v1
	s_mul_i32 s13, s13, s16
	s_mul_hi_u32 s13, s16, s13
	s_add_i32 s16, s16, s13
	s_mul_hi_u32 s13, s5, s16
	s_mul_i32 s16, s13, s11
	s_sub_i32 s5, s5, s16
	s_add_i32 s17, s13, 1
	s_sub_i32 s16, s5, s11
	s_cmp_ge_u32 s5, s11
	s_cselect_b32 s13, s17, s13
	s_cselect_b32 s5, s16, s5
	s_add_i32 s16, s13, 1
	s_cmp_ge_u32 s5, s11
	s_cselect_b32 s5, s16, s13
	s_xor_b32 s5, s5, s12
	s_sub_i32 s5, s5, s12
	s_mul_i32 s10, s5, s10
	s_sub_i32 s2, s2, s10
	s_add_i32 s9, s9, s2
	s_lshl_b32 s2, s9, 8
	s_or_b32 s2, s5, s2
	s_or_b32 s10, s2, 0x80200000

;     __host__ __device__ __forceinline__ bool next(int i, Unit& u) const {
;         const long L = (long)i * G + c; if (L >= nwg) return false;
;         int wgid = (int)L; { const int q = nwg / NXCD, r = nwg % NXCD, xcd = wgid % NXCD, off = wgid / NXCD; wgid = (xcd < r ? xcd * (q + 1) : r * (q + 1) + (xcd - r) * q) + off; }
;         const int nig = WGM * nN, gid = wgid / nig, fm = gid * WGM, gsz = (nM - fm) < WGM ? (nM - fm) : WGM;
;         u.pm = fm + ((wgid % nig) % gsz); u.pn = (wgid % nig) / gsz; u.ko = 0; u.nk = nk; return true;
;     }
; template <class Epi, class Sched, bool ALIGN_EPI = false, bool SP2 = false>
; __device__ __forceinline__ void gemm_phase(PG8_LAS unsigned char* lds, const Gemm g, const Sched& S, const Epi& E, const int wv) {
;     ...
;         nxt = cur; bool has_next; PG8_NEXT(ui + 1, nxt, has_next);
.LBB0_1169:
	s_add_i32 s58, s58, 1
	s_mul_i32 s2, s58, s56
	s_mul_hi_u32 s16, s58, s70
	s_add_i32 s2, s16, s2
	s_mul_i32 s16, s58, s70
	s_add_u32 s16, s16, s92
	s_addc_u32 s17, s2, s90
	v_mov_b64_e32 v[0:1], s[6:7]
	v_cmp_ge_i64_e32 vcc, s[16:17], v[0:1]
	s_mov_b32 s18, 0
	s_cbranch_vccnz .LBB0_1171
	s_ashr_i32 s2, s16, 31
	s_lshr_b32 s2, s2, 29
	s_add_i32 s2, s16, s2
	s_ashr_i32 s17, s2, 3
	s_and_b32 s2, s2, -8
	s_sub_i32 s2, s16, s2
	s_cmpk_lt_i32 s17, 0x160
	s_cselect_b32 s16, 0x160, 22
	s_mul_i32 s2, s16, s2
	s_cselect_b32 s16, 0, 0x9a0
	s_add_i32 s2, s2, s17
	s_add_i32 s2, s2, s16
	s_mul_hi_i32 s16, s2, 0x2e8ba2e9
	s_lshr_b32 s17, s16, 31
	s_ashr_i32 s16, s16, 6
	s_add_i32 s16, s16, s17
	s_lshl_b32 s17, s16, 3
	s_sub_i32 s18, s4, s17
	s_min_i32 s18, s18, 8
	s_abs_i32 s19, s18
	v_cvt_f32_u32_e32 v0, s19
	s_sub_i32 s21, 0, s19
	s_mulk_i32 s16, 0x160
	s_sub_i32 s2, s2, s16
	v_rcp_iflag_f32_e32 v0, v0
	s_abs_i32 s16, s2
	s_xor_b32 s20, s2, s18
	s_ashr_i32 s20, s20, 31
	v_mul_f32_e32 v0, 0x4f7ffffe, v0
	v_cvt_u32_f32_e32 v0, v0
	s_nop 0
	v_readfirstlane_b32 s26, v0
	s_mul_i32 s21, s21, s26
	s_mul_hi_u32 s21, s26, s21
	s_add_i32 s26, s26, s21
	s_mul_hi_u32 s21, s16, s26
	s_mul_i32 s26, s21, s19
	s_sub_i32 s16, s16, s26
	s_add_i32 s27, s21, 1
	s_sub_i32 s26, s16, s19
	s_cmp_ge_u32 s16, s19
	s_cselect_b32 s21, s27, s21
	s_cselect_b32 s16, s26, s16
	s_add_i32 s26, s21, 1
	s_cmp_ge_u32 s16, s19
	s_cselect_b32 s16, s26, s21
	s_xor_b32 s16, s16, s20
	s_sub_i32 s16, s16, s20
	s_mul_i32 s18, s16, s18
	s_sub_i32 s2, s2, s18
	s_add_i32 s2, s2, s17
	s_lshl_b32 s2, s2, 8
	s_or_b32 s2, s16, s2
	s_or_b32 s18, s2, 0x80200000
